# phase 0: the activation-row items no longer drain the previous item's stores before issuing their loads
# baseline (speedup 1.0000x reference)
; DEVINL int tidx() { int t = threadIdx.x; asm volatile("" : "+v"(t)); return t; }
; DEVINL int bidx() { int t = blockIdx.x; asm volatile("" : "+s"(t)); return t; }
; DEVINL const float* xrow_ptr(const Params& p, int r) {
;   if (r < MPROMPT) {
;     int b = r / LP, t = r - b * LP;
;     return (t < NMETA) ? (p.meta + (size_t)t * DM) : (p.x_prompt + ((size_t)b * SEQ + (t - NMETA)) * DM);
;   }
;   return p.x_sample + (size_t)(r - MPROMPT) * DM;
; }
; DEVINL void phase0(const Params& p, char* smem) {
;   for (int it = bidx(); it < NTR_A + NXROW_ITEMS + 8; it += gridDim.x) {
;     if (it < NTR_A) {
;       tr_tile(p, smem, 0, it / 16, it % 16);
;     } else if (it < NTR_A + NXROW_ITEMS) {
;       xrow_prep<4>(p, (it - NTR_A) * 16 + (tidx() >> 6) * 4);
.LBB0_1475:
	s_andn2_saveexec_b64 s[36:37], s[44:45]
	s_cbranch_execz .LBB0_1544
	v_mov_b32_e32 v3, v0
	s_waitcnt lgkmcnt(0)
	v_lshlrev_b32_e32 v4, 4, v1
	v_ashrrev_i32_e32 v3, 4, v3
	s_waitcnt lgkmcnt(0)
	v_and_b32_e32 v5, -4, v3
	s_movk_i32 s0, 0xde00
	v_add3_u32 v74, v4, v5, s0
	s_movk_i32 s0, 0x407f
	v_mov_b32_e32 v10, v0
	v_cmp_lt_i32_e32 vcc, s0, v74
	s_and_saveexec_b64 s[0:1], vcc
	s_xor_b64 s[0:1], exec, s[0:1]
	v_add_u32_e32 v4, 0xffffbf80, v74
	v_mov_b32_e32 v5, v2
	s_or_saveexec_b64 s[34:35], s[0:1]
	v_mov_b64_e32 v[6:7], s[54:55]
	s_xor_b64 exec, exec, s[34:35]
	s_cbranch_execz .LBB0_1484
	s_mov_b32 s0, 0xfe03f81
	v_mul_hi_i32 v4, v74, s0
	v_lshrrev_b32_e32 v5, 31, v4
	v_ashrrev_i32_e32 v4, 7, v4
	v_add_u32_e32 v8, v4, v5
	s_movk_i32 s0, 0xf7f0
	v_mad_i32_i24 v4, v8, s0, v74
	v_cmp_lt_i32_e32 vcc, 15, v4
	v_mov_b64_e32 v[6:7], s[62:63]
	s_and_saveexec_b64 s[0:1], vcc
	s_xor_b64 s[0:1], exec, s[0:1]
	v_ashrrev_i32_e32 v9, 31, v8
	v_lshlrev_b64 v[6:7], 23, v[8:9]
	v_add_u32_e32 v4, -16, v4
	v_mov_b32_e32 v5, v2
	v_lshl_add_u64 v[6:7], s[52:53], 0, v[6:7]
	s_andn2_saveexec_b64 s[0:1], s[0:1]
	v_ashrrev_i32_e32 v5, 31, v4
	s_or_b64 exec, exec, s[0:1]
